# conv+gelu phase: issue the 8 row loads of each 4-row body together (one wait) instead of one load per wait
# speedup vs baseline: 1.0326x; 1.0117x over previous
.LBB0_35:
	v_lshl_add_u64 v[32:33], v[24:25], 0, v[0:1]
	s_mov_b64 s[20:21], 0x22000000
	v_lshl_add_u64 v[218:219], v[32:33], 0, s[20:21]
	s_mov_b64 s[20:21], 0x2000
	global_load_dwordx4 v[220:223], v[218:219], off nt
	v_lshl_add_u64 v[218:219], v[218:219], 0, s[20:21]
	global_load_dwordx4 v[224:227], v[218:219], off nt
	v_lshl_add_u64 v[218:219], v[218:219], 0, s[20:21]
	global_load_dwordx4 v[228:231], v[218:219], off nt
	v_lshl_add_u64 v[218:219], v[218:219], 0, s[20:21]
	global_load_dwordx4 v[232:235], v[218:219], off nt
	v_lshl_add_u64 v[218:219], v[218:219], 0, s[20:21]
	global_load_dwordx4 v[236:239], v[218:219], off nt
	v_lshl_add_u64 v[218:219], v[218:219], 0, s[20:21]
	global_load_dwordx4 v[240:243], v[218:219], off nt
	v_lshl_add_u64 v[218:219], v[218:219], 0, s[20:21]
	global_load_dwordx4 v[244:247], v[218:219], off nt
	v_lshl_add_u64 v[218:219], v[218:219], 0, s[20:21]
	global_load_dwordx4 v[248:251], v[218:219], off nt
	s_waitcnt vmcnt(0)
	s_mov_b32 s5, 0x22000000
	v_add_co_u32_e32 v40, vcc, s5, v32
	s_mov_b32 s5, 0x22002000
	s_nop 0
	v_addc_co_u32_e32 v41, vcc, 0, v33, vcc
	v_mov_b64_e32 v[120:121], v[220:221]
	v_mov_b64_e32 v[122:123], v[222:223]
	v_add_co_u32_e32 v40, vcc, s5, v32
	v_pk_fma_f32 v[110:111], v[4:5], v[110:111], v[76:77]
	s_nop 0
	v_addc_co_u32_e32 v41, vcc, 0, v33, vcc
	v_pk_fma_f32 v[110:111], v[78:79], v[94:95], v[110:111]
	v_pk_fma_f32 v[112:113], v[2:3], v[112:113], v[10:11]
	v_pk_fma_f32 v[108:109], v[18:19], v[108:109], v[58:59]
	v_pk_fma_f32 v[112:113], v[26:27], v[96:97], v[112:113]
	v_pk_fma_f32 v[108:109], v[34:35], v[92:93], v[108:109]
	v_pk_fma_f32 v[106:107], v[70:71], v[106:107], v[68:69]
	v_pk_fma_f32 v[102:103], v[8:9], v[102:103], v[44:45]
	v_pk_fma_f32 v[106:107], v[72:73], v[90:91], v[106:107]
	v_pk_fma_f32 v[102:103], v[52:53], v[86:87], v[102:103]
	v_pk_fma_f32 v[104:105], v[6:7], v[104:105], v[14:15]
	v_pk_fma_f32 v[100:101], v[22:23], v[100:101], v[62:63]
	v_pk_fma_f32 v[104:105], v[30:31], v[88:89], v[104:105]
	v_pk_fma_f32 v[100:101], v[38:39], v[84:85], v[100:101]
	v_pk_fma_f32 v[98:99], v[20:21], v[98:99], v[12:13]
	s_mov_b32 s5, 0x1a000000
	v_pk_fma_f32 v[98:99], v[28:29], v[82:83], v[98:99]
	v_pk_fma_f32 v[94:95], v[4:5], v[94:95], v[76:77]
	v_pk_fma_f32 v[96:97], v[2:3], v[96:97], v[10:11]
	v_pk_fma_f32 v[92:93], v[18:19], v[92:93], v[58:59]
	v_pk_fma_f32 v[90:91], v[70:71], v[90:91], v[68:69]
	v_pk_fma_f32 v[86:87], v[8:9], v[86:87], v[44:45]
	v_pk_fma_f32 v[88:89], v[6:7], v[88:89], v[14:15]
	v_pk_fma_f32 v[84:85], v[22:23], v[84:85], v[62:63]
	v_pk_fma_f32 v[82:83], v[20:21], v[82:83], v[12:13]
	s_mov_b64 s[16:17], 0x8000
	s_add_i32 s4, s4, -4
	s_cmp_lg_u32 s4, 0
	v_lshlrev_b32_e32 v56, 16, v122
	v_and_b32_e32 v48, 0xffff0000, v122
	v_lshlrev_b32_e32 v57, 16, v123
	v_and_b32_e32 v49, 0xffff0000, v123
	v_mov_b64_e32 v[122:123], v[224:225]
	v_mov_b64_e32 v[124:125], v[226:227]
	v_and_b32_e32 v116, 0xffff0000, v120
	v_and_b32_e32 v117, 0xffff0000, v121
	v_pk_fma_f32 v[110:111], v[80:81], v[116:117], v[110:111]
	v_lshlrev_b32_e32 v119, 16, v121
	v_lshlrev_b32_e32 v118, 16, v120
	v_pk_fma_f32 v[112:113], v[42:43], v[118:119], v[112:113]
	v_pk_fma_f32 v[102:103], v[60:61], v[48:49], v[102:103]
	v_pk_fma_f32 v[104:105], v[46:47], v[56:57], v[104:105]
	v_pk_fma_f32 v[94:95], v[78:79], v[116:117], v[94:95]
	v_pk_fma_f32 v[96:97], v[26:27], v[118:119], v[96:97]
	v_pk_fma_f32 v[86:87], v[52:53], v[48:49], v[86:87]
	v_pk_fma_f32 v[88:89], v[30:31], v[56:57], v[88:89]
	v_pk_fma_f32 v[48:49], v[8:9], v[48:49], v[44:45]
	v_pk_fma_f32 v[56:57], v[6:7], v[56:57], v[14:15]
	v_lshlrev_b32_e32 v121, 16, v123
	v_and_b32_e32 v115, 0xffff0000, v123
	v_mul_f32_e32 v123, 0x3d372713, v110
	v_mul_f32_e32 v123, v110, v123
	v_fma_f32 v123, v110, v123, v110
	v_mul_f32_e32 v123, 0x3f4c422a, v123
	v_mul_f32_e32 v123, 0x4038aa3b, v123
	v_exp_f32_e32 v123, v123
	v_lshlrev_b32_e32 v120, 16, v122
	v_and_b32_e32 v114, 0xffff0000, v122
	v_lshlrev_b32_e32 v64, 16, v124
	v_add_f32_e32 v123, 1.0, v123
	v_and_b32_e32 v40, 0xffff0000, v124
	v_mul_f32_e32 v122, 0x3d372713, v112
	v_rcp_f32_e32 v124, v123
	v_mul_f32_e32 v123, 0x3d372713, v113
	v_mul_f32_e32 v122, v112, v122
	v_mul_f32_e32 v123, v113, v123
	v_fma_f32 v122, v112, v122, v112
	v_fma_f32 v123, v113, v123, v113
	v_mul_f32_e32 v122, 0x3f4c422a, v122
	v_mul_f32_e32 v123, 0x3f4c422a, v123
	v_mul_f32_e32 v122, 0x4038aa3b, v122
	v_mul_f32_e32 v123, 0x4038aa3b, v123
	v_exp_f32_e32 v122, v122
	v_exp_f32_e32 v123, v123
	v_pk_mul_f32 v[112:113], v[112:113], 0.5 op_sel_hi:[1,0]
	v_pk_fma_f32 v[108:109], v[50:51], v[120:121], v[108:109]
	v_add_f32_e32 v122, 1.0, v122
	v_add_f32_e32 v123, 1.0, v123
	v_rcp_f32_e32 v122, v122
	v_rcp_f32_e32 v123, v123
	v_lshlrev_b32_e32 v65, 16, v125
	v_and_b32_e32 v41, 0xffff0000, v125
	v_pk_fma_f32 v[106:107], v[74:75], v[114:115], v[106:107]
	v_pk_fma_f32 v[122:123], v[122:123], 2.0, 1.0 op_sel_hi:[1,0,0] neg_lo:[1,0,0] neg_hi:[1,0,0]
	v_pk_fma_f32 v[100:101], v[54:55], v[64:65], v[100:101]
	v_pk_add_f32 v[122:123], v[122:123], 1.0 op_sel_hi:[1,0]
	v_pk_fma_f32 v[98:99], v[36:37], v[40:41], v[98:99]
	v_pk_mul_f32 v[112:113], v[112:113], v[122:123]
	v_lshl_add_u64 v[122:123], v[16:17], 0, v[0:1]
	v_pk_mul_f32 v[108:109], v[108:109], v[112:113]
	v_mul_f32_e32 v112, 0x3d372713, v111
	v_mul_f32_e32 v112, v111, v112
	v_fma_f32 v112, v111, v112, v111
	v_mul_f32_e32 v112, 0x3f4c422a, v112
	v_mul_f32_e32 v112, 0x4038aa3b, v112
	v_exp_f32_e32 v112, v112
	v_pk_mul_f32 v[110:111], v[110:111], 0.5 op_sel_hi:[1,0]
	v_pk_fma_f32 v[92:93], v[34:35], v[120:121], v[92:93]
	v_pk_fma_f32 v[90:91], v[72:73], v[114:115], v[90:91]
	v_add_f32_e32 v112, 1.0, v112
	v_rcp_f32_e32 v125, v112
	v_pk_fma_f32 v[84:85], v[38:39], v[64:65], v[84:85]
	v_pk_fma_f32 v[82:83], v[28:29], v[40:41], v[82:83]
	v_pk_fma_f32 v[64:65], v[22:23], v[64:65], v[62:63]
	v_pk_fma_f32 v[112:113], v[124:125], 2.0, 1.0 op_sel_hi:[1,0,0] neg_lo:[1,0,0] neg_hi:[1,0,0]
	v_pk_fma_f32 v[40:41], v[20:21], v[40:41], v[12:13]
	v_pk_add_f32 v[112:113], v[112:113], 1.0 op_sel_hi:[1,0]
	v_lshl_add_u64 v[16:17], v[16:17], 0, s[16:17]
	v_pk_mul_f32 v[110:111], v[110:111], v[112:113]
	s_mov_b64 s[16:17], 0x10000
	v_pk_mul_f32 v[106:107], v[106:107], v[110:111]
	v_mul_f32_e32 v111, 0x3d372713, v102
	v_mul_f32_e32 v111, v102, v111
	v_fma_f32 v111, v102, v111, v102
	v_mul_f32_e32 v111, 0x3f4c422a, v111
	v_mul_f32_e32 v111, 0x4038aa3b, v111
	v_exp_f32_e32 v111, v111
	v_mul_f32_e32 v110, 0x3d372713, v104
	v_mul_f32_e32 v110, v104, v110
	v_fma_f32 v110, v104, v110, v104
	v_add_f32_e32 v111, 1.0, v111
	v_rcp_f32_e32 v112, v111
	v_mul_f32_e32 v111, 0x3d372713, v105
	v_mul_f32_e32 v111, v105, v111
	v_fma_f32 v111, v105, v111, v105
	v_mul_f32_e32 v110, 0x3f4c422a, v110
	v_mul_f32_e32 v111, 0x3f4c422a, v111
	v_mul_f32_e32 v110, 0x4038aa3b, v110
	v_mul_f32_e32 v111, 0x4038aa3b, v111
	v_exp_f32_e32 v110, v110
	v_exp_f32_e32 v111, v111
	v_pk_mul_f32 v[104:105], v[104:105], 0.5 op_sel_hi:[1,0]
	v_lshl_add_u64 v[24:25], v[24:25], 0, s[16:17]
	v_add_f32_e32 v110, 1.0, v110
	v_add_f32_e32 v111, 1.0, v111
	v_rcp_f32_e32 v110, v110
	v_rcp_f32_e32 v111, v111
	s_nop 0
	v_pk_fma_f32 v[110:111], v[110:111], 2.0, 1.0 op_sel_hi:[1,0,0] neg_lo:[1,0,0] neg_hi:[1,0,0]
	s_nop 0
	v_pk_add_f32 v[110:111], v[110:111], 1.0 op_sel_hi:[1,0]
	s_nop 0
	v_pk_mul_f32 v[104:105], v[104:105], v[110:111]
	s_nop 0
	v_pk_mul_f32 v[100:101], v[100:101], v[104:105]
	v_mul_f32_e32 v104, 0x3d372713, v103
	v_mul_f32_e32 v104, v103, v104
	v_fma_f32 v104, v103, v104, v103
	v_mul_f32_e32 v104, 0x3f4c422a, v104
	v_mul_f32_e32 v104, 0x4038aa3b, v104
	v_exp_f32_e32 v104, v104
	v_pk_mul_f32 v[102:103], v[102:103], 0.5 op_sel_hi:[1,0]
	v_add_f32_e32 v104, 1.0, v104
	v_rcp_f32_e32 v113, v104
	s_nop 0
	v_pk_fma_f32 v[104:105], v[112:113], 2.0, 1.0 op_sel_hi:[1,0,0] neg_lo:[1,0,0] neg_hi:[1,0,0]
	s_nop 0
	v_pk_add_f32 v[104:105], v[104:105], 1.0 op_sel_hi:[1,0]
	s_nop 0
	v_pk_mul_f32 v[102:103], v[102:103], v[104:105]
	v_bfe_u32 v105, v106, 16, 1
	v_pk_mul_f32 v[98:99], v[98:99], v[102:103]
	v_bfe_u32 v104, v107, 16, 1
	v_bfe_u32 v102, v99, 16, 1
	v_bfe_u32 v103, v98, 16, 1
	v_add3_u32 v105, v106, v105, s68
	v_add3_u32 v99, v99, v102, s68
	v_bfe_u32 v102, v108, 16, 1
	v_bfe_u32 v106, v100, 16, 1
	v_add3_u32 v104, v107, v104, s68
	v_add3_u32 v98, v98, v103, s68
	v_bfe_u32 v103, v109, 16, 1
	v_bfe_u32 v107, v101, 16, 1
	v_add3_u32 v100, v100, v106, s68
	v_add3_u32 v102, v108, v102, s68
	v_add3_u32 v101, v101, v107, s68
	v_add3_u32 v103, v109, v103, s68
	v_lshrrev_b32_e32 v102, 16, v102
	v_lshrrev_b32_e32 v100, 16, v100
	v_lshrrev_b32_e32 v103, 16, v103
	v_lshrrev_b32_e32 v101, 16, v101
	v_and_or_b32 v100, v98, s69, v100
	v_and_or_b32 v98, v105, s69, v102
	v_add_co_u32_e32 v102, vcc, s5, v122
	v_and_or_b32 v101, v99, s69, v101
	v_and_or_b32 v99, v104, s69, v103
	v_addc_co_u32_e32 v103, vcc, 0, v123, vcc
	s_mov_b32 s5, 0x22004000
	flat_store_dwordx4 v[102:103], v[98:101]
	s_nop 1
	v_add_co_u32_e32 v98, vcc, s5, v32
	s_mov_b32 s5, 0x22006000
	s_nop 0
	v_addc_co_u32_e32 v99, vcc, 0, v33, vcc
	v_mov_b64_e32 v[98:99], v[228:229]
	v_mov_b64_e32 v[100:101], v[230:231]
	v_lshlrev_b32_e32 v136, 16, v98
	v_and_b32_e32 v134, 0xffff0000, v98
	v_add_co_u32_e32 v98, vcc, s5, v32
	v_lshlrev_b32_e32 v137, 16, v99
	v_and_b32_e32 v135, 0xffff0000, v99
	v_addc_co_u32_e32 v99, vcc, 0, v33, vcc
	v_lshlrev_b32_e32 v128, 16, v100
	v_and_b32_e32 v126, 0xffff0000, v100
	v_lshlrev_b32_e32 v129, 16, v101
	v_and_b32_e32 v127, 0xffff0000, v101
	v_mov_b64_e32 v[98:99], v[232:233]
	v_mov_b64_e32 v[100:101], v[234:235]
	v_pk_fma_f32 v[94:95], v[80:81], v[134:135], v[94:95]
	v_pk_fma_f32 v[96:97], v[42:43], v[136:137], v[96:97]
	v_pk_fma_f32 v[86:87], v[60:61], v[126:127], v[86:87]
	v_pk_fma_f32 v[88:89], v[46:47], v[128:129], v[88:89]
	s_mov_b32 s5, 0x1a002000
	v_pk_fma_f32 v[48:49], v[52:53], v[126:127], v[48:49]
	v_pk_fma_f32 v[56:57], v[30:31], v[128:129], v[56:57]
	v_lshlrev_b32_e32 v139, 16, v99
	v_and_b32_e32 v133, 0xffff0000, v99
	v_mul_f32_e32 v99, 0x3d372713, v94
	v_mul_f32_e32 v99, v94, v99
	v_fma_f32 v99, v94, v99, v94
	v_mul_f32_e32 v99, 0x3f4c422a, v99
	v_mul_f32_e32 v99, 0x4038aa3b, v99
	v_exp_f32_e32 v99, v99
	v_lshlrev_b32_e32 v138, 16, v98
	v_and_b32_e32 v132, 0xffff0000, v98
	v_lshlrev_b32_e32 v130, 16, v100
	v_add_f32_e32 v99, 1.0, v99
	v_and_b32_e32 v124, 0xffff0000, v100
	v_mul_f32_e32 v98, 0x3d372713, v96
	v_rcp_f32_e32 v100, v99
	v_mul_f32_e32 v99, 0x3d372713, v97
	v_mul_f32_e32 v98, v96, v98
	v_mul_f32_e32 v99, v97, v99
	v_fma_f32 v98, v96, v98, v96
	v_fma_f32 v99, v97, v99, v97
	v_mul_f32_e32 v98, 0x3f4c422a, v98
	v_mul_f32_e32 v99, 0x3f4c422a, v99
	v_mul_f32_e32 v98, 0x4038aa3b, v98
	v_mul_f32_e32 v99, 0x4038aa3b, v99
	v_exp_f32_e32 v98, v98
	v_exp_f32_e32 v99, v99
	v_pk_mul_f32 v[96:97], v[96:97], 0.5 op_sel_hi:[1,0]
	v_pk_fma_f32 v[92:93], v[50:51], v[138:139], v[92:93]
	v_add_f32_e32 v98, 1.0, v98
	v_add_f32_e32 v99, 1.0, v99
	v_rcp_f32_e32 v98, v98
	v_rcp_f32_e32 v99, v99
	v_lshlrev_b32_e32 v131, 16, v101
	v_and_b32_e32 v125, 0xffff0000, v101
	v_pk_fma_f32 v[90:91], v[74:75], v[132:133], v[90:91]
	v_pk_fma_f32 v[98:99], v[98:99], 2.0, 1.0 op_sel_hi:[1,0,0] neg_lo:[1,0,0] neg_hi:[1,0,0]
	v_pk_fma_f32 v[84:85], v[54:55], v[130:131], v[84:85]
	v_pk_add_f32 v[98:99], v[98:99], 1.0 op_sel_hi:[1,0]
	v_pk_fma_f32 v[82:83], v[36:37], v[124:125], v[82:83]
	v_pk_mul_f32 v[96:97], v[96:97], v[98:99]
	v_pk_fma_f32 v[64:65], v[38:39], v[130:131], v[64:65]
	v_pk_mul_f32 v[92:93], v[92:93], v[96:97]
	v_mul_f32_e32 v96, 0x3d372713, v95
	v_mul_f32_e32 v96, v95, v96
	v_fma_f32 v96, v95, v96, v95
	v_mul_f32_e32 v96, 0x3f4c422a, v96
	v_mul_f32_e32 v96, 0x4038aa3b, v96
	v_exp_f32_e32 v96, v96
	v_pk_mul_f32 v[94:95], v[94:95], 0.5 op_sel_hi:[1,0]
	v_pk_fma_f32 v[40:41], v[28:29], v[124:125], v[40:41]
	v_add_f32_e32 v96, 1.0, v96
	v_rcp_f32_e32 v101, v96
	s_nop 0
	v_pk_fma_f32 v[96:97], v[100:101], 2.0, 1.0 op_sel_hi:[1,0,0] neg_lo:[1,0,0] neg_hi:[1,0,0]
	s_nop 0
	v_pk_add_f32 v[96:97], v[96:97], 1.0 op_sel_hi:[1,0]
	s_nop 0
	v_pk_mul_f32 v[94:95], v[94:95], v[96:97]
	s_nop 0
	v_pk_mul_f32 v[90:91], v[90:91], v[94:95]
	v_mul_f32_e32 v95, 0x3d372713, v86
	v_mul_f32_e32 v95, v86, v95
	v_fma_f32 v95, v86, v95, v86
	v_mul_f32_e32 v95, 0x3f4c422a, v95
	v_mul_f32_e32 v95, 0x4038aa3b, v95
	v_exp_f32_e32 v95, v95
	v_mul_f32_e32 v94, 0x3d372713, v88
	v_mul_f32_e32 v94, v88, v94
	v_fma_f32 v94, v88, v94, v88
	v_add_f32_e32 v95, 1.0, v95
	v_rcp_f32_e32 v96, v95
	v_mul_f32_e32 v95, 0x3d372713, v89
	v_mul_f32_e32 v95, v89, v95
	v_fma_f32 v95, v89, v95, v89
	v_mul_f32_e32 v94, 0x3f4c422a, v94
	v_mul_f32_e32 v95, 0x3f4c422a, v95
	v_mul_f32_e32 v94, 0x4038aa3b, v94
	v_mul_f32_e32 v95, 0x4038aa3b, v95
	v_exp_f32_e32 v94, v94
	v_exp_f32_e32 v95, v95
	v_pk_mul_f32 v[88:89], v[88:89], 0.5 op_sel_hi:[1,0]
	v_add_f32_e32 v94, 1.0, v94
	v_add_f32_e32 v95, 1.0, v95
	v_rcp_f32_e32 v94, v94
	v_rcp_f32_e32 v95, v95
	s_nop 0
	v_pk_fma_f32 v[94:95], v[94:95], 2.0, 1.0 op_sel_hi:[1,0,0] neg_lo:[1,0,0] neg_hi:[1,0,0]
	s_nop 0
	v_pk_add_f32 v[94:95], v[94:95], 1.0 op_sel_hi:[1,0]
	s_nop 0
	v_pk_mul_f32 v[88:89], v[88:89], v[94:95]
	s_nop 0
	v_pk_mul_f32 v[84:85], v[84:85], v[88:89]
	v_mul_f32_e32 v88, 0x3d372713, v87
	v_mul_f32_e32 v88, v87, v88
	v_fma_f32 v88, v87, v88, v87
	v_mul_f32_e32 v88, 0x3f4c422a, v88
	v_mul_f32_e32 v88, 0x4038aa3b, v88
	v_exp_f32_e32 v88, v88
	v_pk_mul_f32 v[86:87], v[86:87], 0.5 op_sel_hi:[1,0]
	v_add_f32_e32 v88, 1.0, v88
	v_rcp_f32_e32 v97, v88
	s_nop 0
	v_pk_fma_f32 v[88:89], v[96:97], 2.0, 1.0 op_sel_hi:[1,0,0] neg_lo:[1,0,0] neg_hi:[1,0,0]
	s_nop 0
	v_pk_add_f32 v[88:89], v[88:89], 1.0 op_sel_hi:[1,0]
	s_nop 0
	v_pk_mul_f32 v[86:87], v[86:87], v[88:89]
	v_bfe_u32 v89, v90, 16, 1
	v_pk_mul_f32 v[82:83], v[82:83], v[86:87]
	v_bfe_u32 v88, v91, 16, 1
	v_bfe_u32 v86, v83, 16, 1
	v_bfe_u32 v87, v82, 16, 1
	v_add3_u32 v89, v90, v89, s68
	v_add3_u32 v83, v83, v86, s68
	v_bfe_u32 v86, v92, 16, 1
	v_bfe_u32 v90, v84, 16, 1
	v_add3_u32 v88, v91, v88, s68
	v_add3_u32 v82, v82, v87, s68
	v_bfe_u32 v87, v93, 16, 1
	v_bfe_u32 v91, v85, 16, 1
	v_add3_u32 v84, v84, v90, s68
	v_add3_u32 v86, v92, v86, s68
	v_add3_u32 v85, v85, v91, s68
	v_add3_u32 v87, v93, v87, s68
	v_lshrrev_b32_e32 v86, 16, v86
	v_lshrrev_b32_e32 v84, 16, v84
	v_lshrrev_b32_e32 v87, 16, v87
	v_lshrrev_b32_e32 v85, 16, v85
	v_and_or_b32 v84, v82, s69, v84
	v_and_or_b32 v82, v89, s69, v86
	v_add_co_u32_e32 v86, vcc, s5, v122
	v_and_or_b32 v85, v83, s69, v85
	v_and_or_b32 v83, v88, s69, v87
	v_addc_co_u32_e32 v87, vcc, 0, v123, vcc
	s_mov_b32 s5, 0x22008000
	flat_store_dwordx4 v[86:87], v[82:85]
	v_pk_fma_f32 v[86:87], v[4:5], v[116:117], v[76:77]
	v_pk_fma_f32 v[90:91], v[18:19], v[120:121], v[58:59]
	v_add_co_u32_e32 v82, vcc, s5, v32
	s_mov_b32 s5, 0x2200a000
	s_nop 0
	v_addc_co_u32_e32 v83, vcc, 0, v33, vcc
	v_mov_b64_e32 v[82:83], v[236:237]
	v_mov_b64_e32 v[84:85], v[238:239]
	v_pk_fma_f32 v[86:87], v[78:79], v[134:135], v[86:87]
	v_pk_fma_f32 v[90:91], v[34:35], v[138:139], v[90:91]
	v_lshlrev_b32_e32 v112, 16, v82
	v_and_b32_e32 v110, 0xffff0000, v82
	v_add_co_u32_e32 v82, vcc, s5, v32
	v_lshlrev_b32_e32 v113, 16, v83
	v_and_b32_e32 v111, 0xffff0000, v83
	v_addc_co_u32_e32 v83, vcc, 0, v33, vcc
	v_lshlrev_b32_e32 v104, 16, v84
	v_and_b32_e32 v102, 0xffff0000, v84
	v_lshlrev_b32_e32 v105, 16, v85
	v_and_b32_e32 v103, 0xffff0000, v85
	v_mov_b64_e32 v[82:83], v[240:241]
	v_mov_b64_e32 v[84:85], v[242:243]
	v_pk_fma_f32 v[86:87], v[80:81], v[110:111], v[86:87]
	v_pk_fma_f32 v[48:49], v[60:61], v[102:103], v[48:49]
	v_mul_f32_e32 v89, 0x3d372713, v87
	v_mul_f32_e32 v89, v87, v89
	v_fma_f32 v89, v87, v89, v87
	v_mul_f32_e32 v89, 0x3f4c422a, v89
	v_mul_f32_e32 v89, 0x4038aa3b, v89
	v_exp_f32_e32 v89, v89
	v_pk_fma_f32 v[56:57], v[46:47], v[104:105], v[56:57]
	s_mov_b32 s5, 0x1a004000
	v_add_f32_e32 v89, 1.0, v89
	v_rcp_f32_e32 v89, v89
	v_lshlrev_b32_e32 v101, 16, v85
	v_and_b32_e32 v99, 0xffff0000, v85
	v_mul_f32_e32 v85, 0x3d372713, v86
	v_mul_f32_e32 v85, v86, v85
	v_fma_f32 v85, v86, v85, v86
	v_mul_f32_e32 v85, 0x3f4c422a, v85
	v_mul_f32_e32 v85, 0x4038aa3b, v85
	v_exp_f32_e32 v85, v85
	v_lshlrev_b32_e32 v108, 16, v82
	v_and_b32_e32 v106, 0xffff0000, v82
	v_lshlrev_b32_e32 v109, 16, v83
	v_and_b32_e32 v107, 0xffff0000, v83
	v_pk_fma_f32 v[82:83], v[2:3], v[118:119], v[10:11]
	v_add_f32_e32 v85, 1.0, v85
	v_pk_fma_f32 v[82:83], v[26:27], v[136:137], v[82:83]
	v_lshlrev_b32_e32 v100, 16, v84
	v_pk_fma_f32 v[82:83], v[42:43], v[112:113], v[82:83]
	v_and_b32_e32 v98, 0xffff0000, v84
	v_mul_f32_e32 v84, 0x3d372713, v82
	v_rcp_f32_e32 v88, v85
	v_mul_f32_e32 v85, 0x3d372713, v83
	v_mul_f32_e32 v84, v82, v84
	v_mul_f32_e32 v85, v83, v85
	v_fma_f32 v84, v82, v84, v82
	v_fma_f32 v85, v83, v85, v83
	v_mul_f32_e32 v84, 0x3f4c422a, v84
	v_mul_f32_e32 v85, 0x3f4c422a, v85
	v_mul_f32_e32 v84, 0x4038aa3b, v84
	v_mul_f32_e32 v85, 0x4038aa3b, v85
	v_exp_f32_e32 v84, v84
	v_exp_f32_e32 v85, v85
	v_pk_mul_f32 v[82:83], v[82:83], 0.5 op_sel_hi:[1,0]
	v_pk_fma_f32 v[88:89], v[88:89], 2.0, 1.0 op_sel_hi:[1,0,0] neg_lo:[1,0,0] neg_hi:[1,0,0]
	v_add_f32_e32 v84, 1.0, v84
	v_add_f32_e32 v85, 1.0, v85
	v_rcp_f32_e32 v84, v84
	v_rcp_f32_e32 v85, v85
	v_pk_mul_f32 v[86:87], v[86:87], 0.5 op_sel_hi:[1,0]
	v_pk_add_f32 v[88:89], v[88:89], 1.0 op_sel_hi:[1,0]
	v_pk_fma_f32 v[64:65], v[54:55], v[100:101], v[64:65]
	v_pk_fma_f32 v[84:85], v[84:85], 2.0, 1.0 op_sel_hi:[1,0,0] neg_lo:[1,0,0] neg_hi:[1,0,0]
	v_pk_mul_f32 v[86:87], v[86:87], v[88:89]
	v_pk_add_f32 v[84:85], v[84:85], 1.0 op_sel_hi:[1,0]
	v_pk_fma_f32 v[40:41], v[36:37], v[98:99], v[40:41]
	v_pk_mul_f32 v[82:83], v[82:83], v[84:85]
	v_pk_fma_f32 v[84:85], v[70:71], v[114:115], v[68:69]
	v_pk_fma_f32 v[90:91], v[50:51], v[108:109], v[90:91]
	v_pk_fma_f32 v[84:85], v[72:73], v[132:133], v[84:85]
	v_pk_mul_f32 v[82:83], v[90:91], v[82:83]
	v_pk_fma_f32 v[84:85], v[74:75], v[106:107], v[84:85]
	s_nop 0
	v_pk_mul_f32 v[84:85], v[84:85], v[86:87]
	v_mul_f32_e32 v87, 0x3d372713, v48
	v_mul_f32_e32 v87, v48, v87
	v_fma_f32 v87, v48, v87, v48
	v_mul_f32_e32 v87, 0x3f4c422a, v87
	v_mul_f32_e32 v87, 0x4038aa3b, v87
	v_exp_f32_e32 v87, v87
	v_mul_f32_e32 v86, 0x3d372713, v56
	v_mul_f32_e32 v86, v56, v86
	v_fma_f32 v86, v56, v86, v56
	v_add_f32_e32 v87, 1.0, v87
	v_rcp_f32_e32 v88, v87
	v_mul_f32_e32 v87, 0x3d372713, v57
	v_mul_f32_e32 v87, v57, v87
	v_fma_f32 v87, v57, v87, v57
	v_mul_f32_e32 v86, 0x3f4c422a, v86
	v_mul_f32_e32 v87, 0x3f4c422a, v87
	v_mul_f32_e32 v86, 0x4038aa3b, v86
	v_mul_f32_e32 v87, 0x4038aa3b, v87
	v_exp_f32_e32 v86, v86
	v_exp_f32_e32 v87, v87
	v_pk_mul_f32 v[56:57], v[56:57], 0.5 op_sel_hi:[1,0]
	v_add_f32_e32 v86, 1.0, v86
	v_add_f32_e32 v87, 1.0, v87
	v_rcp_f32_e32 v86, v86
	v_rcp_f32_e32 v87, v87
	s_nop 0
	v_pk_fma_f32 v[86:87], v[86:87], 2.0, 1.0 op_sel_hi:[1,0,0] neg_lo:[1,0,0] neg_hi:[1,0,0]
	s_nop 0
	v_pk_add_f32 v[86:87], v[86:87], 1.0 op_sel_hi:[1,0]
	s_nop 0
	v_pk_mul_f32 v[56:57], v[56:57], v[86:87]
	s_nop 0
	v_pk_mul_f32 v[56:57], v[64:65], v[56:57]
	v_mul_f32_e32 v64, 0x3d372713, v49
	v_mul_f32_e32 v64, v49, v64
	v_fma_f32 v64, v49, v64, v49
	v_mul_f32_e32 v64, 0x3f4c422a, v64
	v_mul_f32_e32 v64, 0x4038aa3b, v64
	v_exp_f32_e32 v64, v64
	v_pk_mul_f32 v[48:49], v[48:49], 0.5 op_sel_hi:[1,0]
	v_add_f32_e32 v64, 1.0, v64
	v_rcp_f32_e32 v89, v64
	s_nop 0
	v_pk_fma_f32 v[64:65], v[88:89], 2.0, 1.0 op_sel_hi:[1,0,0] neg_lo:[1,0,0] neg_hi:[1,0,0]
	s_nop 0
	v_pk_add_f32 v[64:65], v[64:65], 1.0 op_sel_hi:[1,0]
	s_nop 0
	v_pk_mul_f32 v[48:49], v[48:49], v[64:65]
	v_bfe_u32 v65, v84, 16, 1
	v_pk_mul_f32 v[40:41], v[40:41], v[48:49]
	v_bfe_u32 v64, v85, 16, 1
	v_bfe_u32 v48, v41, 16, 1
	v_bfe_u32 v49, v40, 16, 1
	v_add3_u32 v65, v84, v65, s68
	v_bfe_u32 v84, v56, 16, 1
	v_add3_u32 v64, v85, v64, s68
	v_add3_u32 v40, v40, v49, s68
	v_add3_u32 v41, v41, v48, s68
	v_bfe_u32 v48, v82, 16, 1
	v_bfe_u32 v49, v83, 16, 1
	v_bfe_u32 v85, v57, 16, 1
	v_add3_u32 v56, v56, v84, s68
	v_add3_u32 v57, v57, v85, s68
	v_add3_u32 v49, v83, v49, s68
	v_add3_u32 v48, v82, v48, s68
	v_lshrrev_b32_e32 v56, 16, v56
	v_lshrrev_b32_e32 v48, 16, v48
	v_lshrrev_b32_e32 v49, 16, v49
	v_lshrrev_b32_e32 v57, 16, v57
	v_and_or_b32 v84, v40, s69, v56
	v_add_co_u32_e32 v40, vcc, s5, v122
	v_and_or_b32 v85, v41, s69, v57
	v_and_or_b32 v83, v64, s69, v49
	v_and_or_b32 v82, v65, s69, v48
	v_addc_co_u32_e32 v41, vcc, 0, v123, vcc
	s_mov_b32 s5, 0x2200c000
	flat_store_dwordx4 v[40:41], v[82:85]
	v_add_co_u32_e32 v40, vcc, s5, v32
	s_mov_b32 s5, 0x2200e000
	s_nop 0
	v_addc_co_u32_e32 v41, vcc, 0, v33, vcc
	v_mov_b64_e32 v[82:83], v[244:245]
	v_mov_b64_e32 v[84:85], v[246:247]
	v_add_co_u32_e32 v32, vcc, s5, v32
	v_pk_fma_f32 v[48:49], v[4:5], v[134:135], v[76:77]
	s_nop 0
	v_addc_co_u32_e32 v33, vcc, 0, v33, vcc
	v_mov_b64_e32 v[114:115], v[248:249]
	v_mov_b64_e32 v[116:117], v[250:251]
	v_pk_fma_f32 v[48:49], v[78:79], v[110:111], v[48:49]
	v_pk_fma_f32 v[32:33], v[2:3], v[136:137], v[10:11]
	v_pk_fma_f32 v[64:65], v[18:19], v[138:139], v[58:59]
	v_pk_fma_f32 v[32:33], v[26:27], v[112:113], v[32:33]
	v_pk_fma_f32 v[64:65], v[34:35], v[108:109], v[64:65]
	v_and_b32_e32 v94, 0xffff0000, v82
	v_and_b32_e32 v95, 0xffff0000, v83
	v_pk_fma_f32 v[48:49], v[80:81], v[94:95], v[48:49]
	v_lshlrev_b32_e32 v96, 16, v82
	v_mul_f32_e32 v41, 0x3d372713, v48
	v_mul_f32_e32 v41, v48, v41
	v_fma_f32 v41, v48, v41, v48
	v_mul_f32_e32 v41, 0x3f4c422a, v41
	v_mul_f32_e32 v41, 0x4038aa3b, v41
	v_exp_f32_e32 v41, v41
	v_lshlrev_b32_e32 v97, 16, v83
	v_pk_fma_f32 v[32:33], v[42:43], v[96:97], v[32:33]
	v_mul_f32_e32 v57, 0x3d372713, v49
	v_add_f32_e32 v41, 1.0, v41
	v_mul_f32_e32 v40, 0x3d372713, v32
	v_rcp_f32_e32 v56, v41
	v_mul_f32_e32 v41, 0x3d372713, v33
	v_mul_f32_e32 v40, v32, v40
	v_mul_f32_e32 v41, v33, v41
	v_fma_f32 v40, v32, v40, v32
	v_fma_f32 v41, v33, v41, v33
	v_mul_f32_e32 v40, 0x3f4c422a, v40
	v_mul_f32_e32 v41, 0x3f4c422a, v41
	v_mul_f32_e32 v40, 0x4038aa3b, v40
	v_mul_f32_e32 v41, 0x4038aa3b, v41
	v_exp_f32_e32 v40, v40
	v_exp_f32_e32 v41, v41
	v_mul_f32_e32 v57, v49, v57
	v_fma_f32 v57, v49, v57, v49
	v_mul_f32_e32 v57, 0x3f4c422a, v57
	v_mul_f32_e32 v57, 0x4038aa3b, v57
	v_add_f32_e32 v40, 1.0, v40
	v_add_f32_e32 v41, 1.0, v41
	v_exp_f32_e32 v57, v57
	v_rcp_f32_e32 v40, v40
	v_rcp_f32_e32 v41, v41
	v_lshlrev_b32_e32 v92, 16, v114
	v_add_f32_e32 v57, 1.0, v57
	v_rcp_f32_e32 v57, v57
	v_pk_fma_f32 v[40:41], v[40:41], 2.0, 1.0 op_sel_hi:[1,0,0] neg_lo:[1,0,0] neg_hi:[1,0,0]
	v_lshlrev_b32_e32 v93, 16, v115
	v_pk_mul_f32 v[32:33], v[32:33], 0.5 op_sel_hi:[1,0]
	v_pk_add_f32 v[40:41], v[40:41], 1.0 op_sel_hi:[1,0]
	v_pk_fma_f32 v[64:65], v[50:51], v[92:93], v[64:65]
	v_pk_mul_f32 v[32:33], v[32:33], v[40:41]
	v_and_b32_e32 v86, 0xffff0000, v84
	v_pk_mul_f32 v[32:33], v[64:65], v[32:33]
	v_pk_fma_f32 v[64:65], v[8:9], v[126:127], v[44:45]
	v_and_b32_e32 v87, 0xffff0000, v85
	v_pk_fma_f32 v[56:57], v[56:57], 2.0, 1.0 op_sel_hi:[1,0,0] neg_lo:[1,0,0] neg_hi:[1,0,0]
	v_pk_fma_f32 v[64:65], v[52:53], v[102:103], v[64:65]
	v_pk_mul_f32 v[48:49], v[48:49], 0.5 op_sel_hi:[1,0]
	v_pk_add_f32 v[56:57], v[56:57], 1.0 op_sel_hi:[1,0]
	v_pk_fma_f32 v[64:65], v[60:61], v[86:87], v[64:65]
	v_pk_mul_f32 v[48:49], v[48:49], v[56:57]
	v_mul_f32_e32 v57, 0x3d372713, v64
	v_mul_f32_e32 v57, v64, v57
	v_fma_f32 v57, v64, v57, v64
	v_mul_f32_e32 v57, 0x3f4c422a, v57
	v_pk_fma_f32 v[40:41], v[70:71], v[132:133], v[68:69]
	v_mul_f32_e32 v57, 0x4038aa3b, v57
	v_and_b32_e32 v90, 0xffff0000, v114
	v_and_b32_e32 v91, 0xffff0000, v115
	v_pk_fma_f32 v[40:41], v[72:73], v[106:107], v[40:41]
	v_exp_f32_e32 v57, v57
	v_pk_fma_f32 v[40:41], v[74:75], v[90:91], v[40:41]
	v_lshlrev_b32_e32 v88, 16, v84
	v_pk_mul_f32 v[40:41], v[40:41], v[48:49]
	v_pk_fma_f32 v[48:49], v[6:7], v[128:129], v[14:15]
	v_lshlrev_b32_e32 v89, 16, v85
	v_pk_fma_f32 v[48:49], v[30:31], v[104:105], v[48:49]
	v_add_f32_e32 v57, 1.0, v57
	v_pk_fma_f32 v[48:49], v[46:47], v[88:89], v[48:49]
	v_rcp_f32_e32 v114, v57
	v_mul_f32_e32 v56, 0x3d372713, v48
	v_mul_f32_e32 v57, 0x3d372713, v49
	v_mul_f32_e32 v56, v48, v56
	v_mul_f32_e32 v57, v49, v57
	v_fma_f32 v56, v48, v56, v48
	v_fma_f32 v57, v49, v57, v49
	v_mul_f32_e32 v115, 0x3d372713, v65
	v_mul_f32_e32 v56, 0x3f4c422a, v56
	v_mul_f32_e32 v57, 0x3f4c422a, v57
	v_mul_f32_e32 v115, v65, v115
	v_mul_f32_e32 v56, 0x4038aa3b, v56
	v_mul_f32_e32 v57, 0x4038aa3b, v57
	v_fma_f32 v115, v65, v115, v65
	v_exp_f32_e32 v56, v56
	v_exp_f32_e32 v57, v57
	v_mul_f32_e32 v115, 0x3f4c422a, v115
	v_mul_f32_e32 v115, 0x4038aa3b, v115
	v_exp_f32_e32 v115, v115
	v_add_f32_e32 v56, 1.0, v56
	v_add_f32_e32 v57, 1.0, v57
	v_rcp_f32_e32 v56, v56
	v_rcp_f32_e32 v57, v57
	v_add_f32_e32 v115, 1.0, v115
	v_rcp_f32_e32 v115, v115
	v_pk_mul_f32 v[48:49], v[48:49], 0.5 op_sel_hi:[1,0]
	v_pk_fma_f32 v[56:57], v[56:57], 2.0, 1.0 op_sel_hi:[1,0,0] neg_lo:[1,0,0] neg_hi:[1,0,0]
	v_and_b32_e32 v82, 0xffff0000, v116
	v_pk_add_f32 v[56:57], v[56:57], 1.0 op_sel_hi:[1,0]
	v_pk_fma_f32 v[114:115], v[114:115], 2.0, 1.0 op_sel_hi:[1,0,0] neg_lo:[1,0,0] neg_hi:[1,0,0]
	v_pk_mul_f32 v[48:49], v[48:49], v[56:57]
	v_pk_fma_f32 v[56:57], v[20:21], v[124:125], v[12:13]
	v_and_b32_e32 v83, 0xffff0000, v117
	v_pk_fma_f32 v[56:57], v[28:29], v[98:99], v[56:57]
	v_pk_mul_f32 v[64:65], v[64:65], 0.5 op_sel_hi:[1,0]
	v_pk_add_f32 v[114:115], v[114:115], 1.0 op_sel_hi:[1,0]
	v_lshlrev_b32_e32 v84, 16, v116
	v_lshlrev_b32_e32 v85, 16, v117
	v_pk_fma_f32 v[116:117], v[22:23], v[130:131], v[62:63]
	v_pk_fma_f32 v[56:57], v[36:37], v[82:83], v[56:57]
	v_pk_mul_f32 v[64:65], v[64:65], v[114:115]
	v_pk_fma_f32 v[116:117], v[38:39], v[100:101], v[116:117]
	v_pk_mul_f32 v[56:57], v[56:57], v[64:65]
	v_pk_fma_f32 v[116:117], v[54:55], v[84:85], v[116:117]
	v_bfe_u32 v64, v57, 16, 1
	v_pk_mul_f32 v[48:49], v[116:117], v[48:49]
	v_bfe_u32 v65, v56, 16, 1
	v_bfe_u32 v114, v41, 16, 1
	v_bfe_u32 v115, v40, 16, 1
	v_add3_u32 v57, v57, v64, s68
	v_bfe_u32 v64, v32, 16, 1
	v_add3_u32 v40, v40, v115, s68
	v_add3_u32 v41, v41, v114, s68
	v_add3_u32 v56, v56, v65, s68
	v_bfe_u32 v65, v33, 16, 1
	v_bfe_u32 v114, v48, 16, 1
	v_bfe_u32 v115, v49, 16, 1
	v_add3_u32 v32, v32, v64, s68
	v_add3_u32 v49, v49, v115, s68
	v_add3_u32 v48, v48, v114, s68
	v_add3_u32 v33, v33, v65, s68
	v_lshrrev_b32_e32 v32, 16, v32
	v_lshrrev_b32_e32 v33, 16, v33
	v_lshrrev_b32_e32 v48, 16, v48
	v_lshrrev_b32_e32 v49, 16, v49
	v_and_or_b32 v114, v40, s69, v32
	v_add_co_u32_e32 v32, vcc, 0x1a006000, v122
	v_and_or_b32 v117, v57, s69, v49
	v_and_or_b32 v116, v56, s69, v48
	v_and_or_b32 v115, v41, s69, v33
	v_addc_co_u32_e32 v33, vcc, 0, v123, vcc
	flat_store_dwordx4 v[32:33], v[114:117]
	s_cbranch_scc1 .LBB0_35
	v_readlane_b32 s4, v252, 44
	v_readlane_b32 s5, v252, 45
	s_nop 0
	v_add_u32_e32 v140, s4, v140
	s_mov_b32 s4, 0x3ffff
	v_cmp_lt_i32_e32 vcc, s4, v140
	v_readlane_b32 s4, v252, 22
	s_or_b64 s[14:15], vcc, s[14:15]
	s_nop 0
	v_add_u32_e32 v141, s4, v141
	s_andn2_b64 exec, exec, s[14:15]
	s_cbranch_execnz .LBB0_32
